# EpiRes epilogue hand-pipelined (batched stat/gate/bias loads, 3 round trips instead of 12, global_ instead of flat_) + phase-0 grid.sync replaced by xcd barrier
# speedup vs baseline: 1.0023x; 1.0023x over previous
; #define LAS __attribute__((address_space(3)))
; __global__ void __launch_bounds__(512, 2) mk_fwd(Args args) {
;     extern __shared__ __attribute__((aligned(16))) unsigned char lds_raw[];
;     LAS unsigned char* lds = (LAS unsigned char*)lds_raw;
;     const int G = gridDim.x, NGW = G * 8;
;     cg::grid_group grid = cg::this_grid();
;     if (threadIdx.x == 0) { ((volatile LAS unsigned*)(lds + LDS_BARST))[0] = 0u; ((volatile LAS unsigned*)(lds + LDS_BARST))[1] = 0u; }
;     __syncthreads();
;     const XcdBarrier xbar = xcd_barrier_post((unsigned*)args.ws, (volatile LAS unsigned*)(lds + LDS_BARST));
;     for (int ph = args.ph_lo; ph < args.ph_hi; ++ph) {
;         unsigned char* ws = args.ws; asm volatile("" : "+s"(ws));
;         float* MODS = (float*)(ws + WS_MODS);
;         float* tabM = (float*)(ws + WS_TAB); float* tabS = tabM + 1024;
;         float* XC = (float*)(ws + WS_XC); float* XL = args.out;
;         bf16_t* WB = (bf16_t*)(ws + WS_W);
;         bf16_t* HO = (bf16_t*)(ws + WS_HO);
;         bf16_t* Z = (bf16_t*)(ws + WS_Z);
;         bf16_t* Q2 = (bf16_t*)(ws + WS_Q2);
;         bf16_t* KV2 = (bf16_t*)(ws + WS_KV2);
;         bf16_t* GB = (bf16_t*)(ws + WS_G);
;         float* HALO = (float*)(ws + WS_HALO);
;         float* STAT = (float*)(ws + WS_STAT);
;         float* SSQ = (float*)(ws + WS_SSQ);
;         int l = 0, kind = 100 + ph;
;         if (ph >= 2) {
;             const unsigned long long SEQ_E = 0x0ull | (1ull << 4) | (2ull << 8) | (3ull << 12) | (4ull << 16) | (9ull << 20) | (5ull << 24) | (6ull << 28) | (7ull << 32) | (8ull << 36) | (10ull << 40);
;             const unsigned long long SEQ_O = 0x0ull | (2ull << 4) | (3ull << 8) | (4ull << 12) | (9ull << 16) | (5ull << 20) | (6ull << 24) | (7ull << 28) | (8ull << 32) | (10ull << 36);
;             const unsigned long long SEQ_L = 0x0ull | (2ull << 4) | (3ull << 8) | (4ull << 12) | (5ull << 16) | (6ull << 20) | (7ull << 24) | (8ull << 28);
;             unsigned long long seq; int pos;
;             if (ph < 13) { l = 0; seq = SEQ_E; pos = ph - 2; } else if (ph < 23) { l = 1; seq = SEQ_O; pos = ph - 13; } else if (ph < 34) { l = 2; seq = SEQ_E; pos = ph - 23; } else { l = 3; seq = SEQ_L; pos = ph - 34; }
;             kind = (int)((seq >> (4 * pos)) & 15ull);
;         }
.LBB0_5:
	s_or_b64 exec, exec, s[4:5]
	s_cmp_ge_i32 s60, s61
	s_cbranch_scc1 .LBB0_863
	s_and_b32 s4, s21, 7
	s_ashr_i32 s5, s62, 3
	s_mul_i32 s4, s5, s4
	s_lshr_b32 s5, s21, 3
	s_ashr_i32 s23, s21, 31
	s_add_i32 s4, s4, s5
	s_lshr_b32 s5, s23, 29
	s_add_i32 s5, s21, s5
	s_ashr_i32 s6, s5, 3
	s_and_b32 s5, s5, -8
	s_lshl_b32 s24, s62, 3
	s_and_b32 s3, s62, 7
	v_writelane_b32 v252, s6, 20
	s_sub_i32 s6, s21, s5
	s_ashr_i32 s22, s62, 31
	s_and_b32 s5, s21, 3
	s_cmp_eq_u32 s5, 0
	s_cselect_b64 s[8:9], -1, 0
	v_writelane_b32 v252, s8, 21
	s_lshl_b32 s5, s21, 3
	s_load_dwordx16 s[36:51], s[0:1], 0x80
	v_writelane_b32 v252, s9, 22
	v_writelane_b32 v252, s5, 23
	s_lshr_b32 s5, s21, 2
	v_writelane_b32 v252, s5, 24
	s_not_b32 s5, s5
	v_writelane_b32 v252, s5, 25
	s_lshr_b32 s5, s22, 30
	s_add_i32 s5, s62, s5
	s_ashr_i32 s5, s5, 2
	v_writelane_b32 v252, s5, 26
	s_sub_i32 s5, s62, s5
	s_lshl_b32 s5, s5, 3
	s_cmpk_lt_i32 s21, 0x300
	v_writelane_b32 v252, s5, 27
	s_cselect_b64 s[8:9], -1, 0
	s_add_i32 s5, s62, -1
	v_writelane_b32 v252, s8, 28
	s_cmp_eq_u32 s21, s5
	v_lshrrev_b32_e32 v1, 20, v0
	v_writelane_b32 v252, s9, 29
	s_cselect_b64 s[8:9], -1, 0
	v_writelane_b32 v252, s8, 30
	v_lshrrev_b32_e32 v0, 10, v0
	v_or_b32_e32 v0, v0, v1
	v_writelane_b32 v252, s9, 31
	s_waitcnt lgkmcnt(0)
	s_add_u32 s8, s50, 0x200
	s_addc_u32 s9, s51, 0
	v_writelane_b32 v252, s8, 32
	s_movk_i32 s83, 0x3ff
	v_and_or_b32 v0, v0, s83, v236
	v_writelane_b32 v252, s9, 33
	s_add_u32 s8, s50, 0x1000
	s_addc_u32 s9, s51, 0
	v_writelane_b32 v252, s8, 34
	s_mov_b32 s80, 0x54442d18
	v_writelane_b32 v254, s21, 0
	v_writelane_b32 v252, s9, 35
	s_add_u32 s8, s50, 0x1100
	s_addc_u32 s9, s51, 0
	v_writelane_b32 v252, s8, 36
	v_mbcnt_lo_u32_b32 v2, -1, 0
	v_mov_b32_e32 v1, 0
	v_writelane_b32 v252, s9, 37
	s_add_u32 s8, s50, 0x1200
	s_addc_u32 s9, s51, 0
	v_writelane_b32 v252, s8, 38
	v_mov_b32_e32 v228, 0x358637bd
	v_mov_b32_e32 v238, 0x260
	v_writelane_b32 v252, s9, 39
	s_add_u32 s8, s50, 0x1300
	s_addc_u32 s9, s51, 0
	v_writelane_b32 v252, s8, 40
	s_cmp_eq_u32 s2, 15
	s_mov_b32 s81, 0x401921fb
	v_writelane_b32 v252, s9, 41
	s_cselect_b64 s[8:9], -1, 0
	v_writelane_b32 v252, s8, 42
	s_cmp_eq_u32 s2, 14
	v_mov_b32_e32 v239, 1
	v_writelane_b32 v252, s9, 43
	s_cselect_b64 s[8:9], -1, 0
	v_writelane_b32 v252, s8, 44
	s_cmp_eq_u32 s2, 13
	v_mov_b32_e32 v229, 0x80
	v_writelane_b32 v252, s9, 45
	s_cselect_b64 s[8:9], -1, 0
	v_writelane_b32 v252, s8, 46
	s_cmp_eq_u32 s2, 12
	v_mov_b32_e32 v241, 0xf149f2ca
	v_writelane_b32 v252, s9, 47
	s_cselect_b64 s[8:9], -1, 0
	v_writelane_b32 v252, s8, 48
	s_cmp_eq_u32 s2, 11
	v_mbcnt_hi_u32_b32 v242, -1, v2
	v_writelane_b32 v252, s9, 49
	s_cselect_b64 s[8:9], -1, 0
	v_writelane_b32 v252, s8, 50
	s_cmp_eq_u32 s2, 10
	v_mov_b32_e32 v230, 0x3b800000
	v_writelane_b32 v252, s9, 51
	s_cselect_b64 s[8:9], -1, 0
	v_writelane_b32 v252, s8, 52
	s_cmp_eq_u32 s2, 9
	v_mov_b32_e32 v244, 0x3b2aaaab
	v_writelane_b32 v252, s9, 53
	s_cselect_b64 s[8:9], -1, 0
	v_writelane_b32 v252, s8, 54
	s_cmp_eq_u32 s2, 8
	v_mov_b32_e32 v245, 0x3e16c740
	v_writelane_b32 v252, s9, 55
	s_cselect_b64 s[8:9], -1, 0
	v_writelane_b32 v252, s8, 56
	s_cmp_eq_u32 s2, 7
	v_mov_b32_e32 v181, 1.0
	v_writelane_b32 v252, s9, 57
	s_cselect_b64 s[8:9], -1, 0
	v_writelane_b32 v252, s8, 58
	s_cmp_eq_u32 s2, 6
	v_mov_b32_e32 v246, 0xb00
	v_writelane_b32 v252, s9, 59
	s_cselect_b64 s[8:9], -1, 0
	v_writelane_b32 v252, s8, 60
	s_cmp_eq_u32 s2, 5
	v_mov_b32_e32 v247, 0x3e38aa3b
	v_writelane_b32 v252, s9, 61
	s_cselect_b64 s[8:9], -1, 0
	v_writelane_b32 v252, s8, 62
	s_cmp_eq_u32 s2, 4
	v_mov_b32_e32 v248, 0x3fe1feb3
	v_writelane_b32 v252, s9, 63
	s_cselect_b64 s[8:9], -1, 0
	v_writelane_b32 v253, s8, 0
	s_cmp_eq_u32 s2, 3
	v_mov_b32_e32 v249, 0x3fd43d13
	v_writelane_b32 v253, s9, 1
	s_cselect_b64 s[8:9], -1, 0
	v_writelane_b32 v253, s8, 2
	s_cmp_eq_u32 s2, 2
	v_mov_b32_e32 v250, 0x3c1c381e
	v_writelane_b32 v253, s9, 3
	s_cselect_b64 s[8:9], -1, 0
	v_writelane_b32 v253, s8, 4
	s_cmp_eq_u32 s2, 1
	v_mov_b32_e32 v251, 0x6248490f
	v_writelane_b32 v253, s9, 5
	s_cselect_b64 s[8:9], -1, 0
	v_writelane_b32 v253, s8, 6
	s_cmp_eq_u32 s2, 0
	s_movk_i32 s90, 0x1200
	v_writelane_b32 v253, s9, 7
	s_cselect_b64 s[8:9], -1, 0
	s_lshl_b32 s2, s2, 8
	s_add_u32 s2, s50, s2
	v_writelane_b32 v253, s8, 8
	s_addc_u32 s5, s51, 0
	s_movk_i32 s33, 0x6000
	v_writelane_b32 v253, s9, 9
	s_add_u32 s8, s2, 0x1400
	s_addc_u32 s9, s5, 0
	v_writelane_b32 v253, s8, 10
	s_movk_i32 s30, 0x50
	s_mov_b32 s28, 0xf800000
	v_writelane_b32 v253, s9, 11
	s_add_u32 s8, s2, 0x2400
	s_addc_u32 s9, s5, 0
	v_writelane_b32 v253, s8, 12
	s_load_dword s2, s[0:1], 0xd0
	s_mov_b32 s29, 0x948000
	v_writelane_b32 v253, s9, 13
	s_add_u32 s8, s50, 0x3400
	s_addc_u32 s9, s51, 0
	v_writelane_b32 v253, s8, 14
	s_waitcnt lgkmcnt(0)
	s_mul_i32 s2, s2, s63
	s_mul_i32 s2, s2, s62
	v_writelane_b32 v253, s9, 15
	s_add_u32 s8, s50, 0x3500
	s_addc_u32 s9, s51, 0
	v_writelane_b32 v253, s8, 16
	s_cmp_eq_u32 s3, 0
	s_mov_b32 s47, 0
	v_writelane_b32 v253, s9, 17
	v_writelane_b32 v253, s2, 18
	s_cselect_b32 s2, s4, s21
	v_writelane_b32 v253, s2, 19
	v_writelane_b32 v253, s6, 20
	s_lshr_b32 s2, s6, 31
	v_writelane_b32 v253, s2, 21
	s_lshl_b32 s2, s21, 11
	v_writelane_b32 v253, s2, 22
	s_lshl_b32 s2, s62, 12
	v_writelane_b32 v253, s2, 23
	s_lshl_b32 s2, s62, 11
	v_writelane_b32 v253, s2, 24
	s_add_i32 s2, 0, 0xa800
	v_writelane_b32 v253, s2, 25
	s_add_i32 s2, 0, 0x22800
	v_writelane_b32 v253, s2, 26
	s_add_i32 s2, 0, 0x22804
	v_writelane_b32 v253, s2, 27
	v_cmp_eq_u32_e64 s[2:3], 0, v0
	s_load_dwordx16 s[4:19], s[0:1], 0x0
	s_ashr_i32 s25, s24, 31
	v_writelane_b32 v253, s2, 28
	s_mov_b64 s[34:35], 0x80
	s_mov_b32 s89, 0xc01921fb
	v_writelane_b32 v253, s3, 29
	s_lshl_b64 s[2:3], s[24:25], 12
	v_writelane_b32 v253, s2, 30
	v_writelane_b32 v254, s24, 1
	s_nop 0
	v_writelane_b32 v253, s3, 31
	s_waitcnt lgkmcnt(0)
	v_writelane_b32 v253, s4, 32
	v_writelane_b32 v254, s25, 2
	v_writelane_b32 v254, s23, 3
	v_writelane_b32 v253, s5, 33
	v_writelane_b32 v253, s6, 34
	v_writelane_b32 v253, s7, 35
	v_writelane_b32 v253, s8, 36
	v_writelane_b32 v253, s9, 37
	v_writelane_b32 v253, s10, 38
	v_writelane_b32 v253, s11, 39
	v_writelane_b32 v253, s12, 40
	v_writelane_b32 v253, s13, 41
	v_writelane_b32 v253, s14, 42
	v_writelane_b32 v253, s15, 43
	v_writelane_b32 v253, s16, 44
	v_writelane_b32 v253, s17, 45
	v_writelane_b32 v253, s18, 46
	v_writelane_b32 v253, s19, 47
	s_load_dwordx16 s[4:19], s[0:1], 0x40
	v_writelane_b32 v254, s22, 4
	s_waitcnt lgkmcnt(0)
	v_writelane_b32 v253, s4, 48
	s_nop 1
	v_writelane_b32 v253, s5, 49
	v_writelane_b32 v253, s6, 50
	v_writelane_b32 v253, s7, 51
	v_writelane_b32 v253, s8, 52
	v_writelane_b32 v253, s9, 53
	v_writelane_b32 v253, s10, 54
	v_writelane_b32 v253, s11, 55
	v_writelane_b32 v253, s12, 56
	v_writelane_b32 v253, s13, 57
	v_writelane_b32 v253, s14, 58
	v_writelane_b32 v253, s15, 59
	v_writelane_b32 v253, s16, 60
	v_writelane_b32 v253, s17, 61
	v_writelane_b32 v253, s18, 62
	v_writelane_b32 v253, s19, 63
	s_branch .LBB0_11
; __global__ void __launch_bounds__(512, 2) mk_fwd(Args args) {
;     ...
;         for (int xs = 0; xs < PROBE_XSYNC; ++xs) xcd_barrier(xbar);
;         if (ph + 1 < args.ph_hi) { if (ph == 0) grid.sync(); else xcd_barrier(xbar); }
.LBB0_9:
	s_mov_b64 s[0:1], 0
	s_waitcnt lgkmcnt(0)

;     __device__ __forceinline__ void operator()(const f32x4 (&acc)[2][2][4][2], const Unit& u, int wr_in, int wc_in, int fr_in, int fq_in) const {
;         int fr = fr_in, fq = fq_in, wr = wr_in, wc = wc_in; asm volatile("" : "+v"(fr), "+v"(fq), "+s"(wr), "+s"(wc));
;         const bool lat = u.pm < 128;
;         const int b = lat ? (u.pm >> 3) : 16;
;         const float* gp = gate + (size_t)b * 6144;
;         const float* src = lat ? srcL : srcC; float* dst = lat ? dstL : dstC;
;         const int rbase = (lat ? u.pm : (u.pm - 128)) * 256 + wr * 64 + 4 * fr;
;         const int colw = u.pn * 256 + wc * 32 + 8 * fq;
; #pragma unroll
;         for (int ai = 0; ai < 2; ++ai) {
;             float sa[4], sb[4];
; #pragma unroll
;             for (int m = 0; m < 4; ++m) { sa[m] = ALPHA; sb[m] = 0.f;
;                 if (stat) { const float2 st = *(const float2*)(stat + 2 * (size_t)(u.pm * 256 + wr * 64 + 4 * fr + ai * 128 + m)); sa[m] = ALPHA * st.y; sb[m] = -sa[m] * st.x; } }
; #pragma unroll
;             for (int bj = 0; bj < 2; ++bj) {
;                 const int col0 = colw + bj * 128;
;                 f32x4 x[4][2];
; #pragma unroll
;                 for (int m = 0; m < 4; ++m) { const float* p = src + (size_t)(rbase + ai * 128 + m) * DM + col0; x[m][0] = *(const f32x4*)(p); x[m][1] = *(const f32x4*)(p + 4); }
;                 const f32x4 g0 = *(const f32x4*)(gp + col0), g1 = *(const f32x4*)(gp + col0 + 4);
;                 f32x4 b0 = (f32x4){0.f, 0.f, 0.f, 0.f}, b1 = b0;
;                 if (bias) { b0 = *(const f32x4*)(bias + col0); b1 = *(const f32x4*)(bias + col0 + 4); }
; #pragma unroll
;                 for (int m = 0; m < 4; ++m) {
;                     float* q = dst + (size_t)(rbase + ai * 128 + m) * DM + col0;
;                     const f32x4 r0 = x[m][0] * sa[m] + sb[m] + g0 * (acc[ai][bj][m][0] + b0), r1 = x[m][1] * sa[m] + sb[m] + g1 * (acc[ai][bj][m][1] + b1);
.LBB0_313:
	v_lshlrev_b32_e64 v178, 6, s4
	s_lshl_b32 s60, s60, 8
	v_lshl_add_u32 v131, v131, 2, v178
	v_add_u32_e32 v200, s60, v131
	v_cndmask_b32_e64 v178, 0, 1, s[90:91]
	v_lshlrev_b32_e32 v179, 3, v130
	v_cmp_ne_u32_e64 s[4:5], 1, v178
	s_lshl_b64 s[52:53], s[52:53], 2
	s_add_u32 s52, s3, s52
	s_addc_u32 s53, s10, s53
	s_add_i32 s63, s60, 0xffff8000
	s_and_b64 s[50:51], s[50:51], exec
	s_cselect_b32 s50, s60, s63
	v_add_u32_e32 v201, s50, v131
	s_lshl_b32 s50, s59, 8
	v_lshlrev_b32_e64 v178, 5, s61
	v_add3_u32 v202, v178, s50, v179
	v_lshlrev_b32_e32 v202, 2, v202
	v_lshlrev_b32_e32 v203, 3, v200
	v_lshl_add_u32 v192, v201, 12, v202
	s_mov_b32 s29, 0x948000
	s_andn2_b64 vcc, exec, s[90:91]
	s_cbranch_vccnz .Lres_nostat
	global_load_dwordx4 v[204:207], v203, s[42:43]
	global_load_dwordx4 v[208:211], v203, s[42:43] offset:16
	global_load_dwordx4 v[212:215], v203, s[42:43] offset:1024
	global_load_dwordx4 v[216:219], v203, s[42:43] offset:1040
	s_branch .Lres_statdone
.Lres_nostat:
	v_mov_b32_e32 v204, 0
	v_mov_b32_e32 v205, 0x3fd744fd
	v_mov_b32_e32 v206, 0
	v_mov_b32_e32 v207, 0x3fd744fd
	v_mov_b32_e32 v208, 0
	v_mov_b32_e32 v209, 0x3fd744fd
	v_mov_b32_e32 v210, 0
	v_mov_b32_e32 v211, 0x3fd744fd
	v_mov_b32_e32 v212, 0
	v_mov_b32_e32 v213, 0x3fd744fd
	v_mov_b32_e32 v214, 0
	v_mov_b32_e32 v215, 0x3fd744fd
	v_mov_b32_e32 v216, 0
	v_mov_b32_e32 v217, 0x3fd744fd
	v_mov_b32_e32 v218, 0
	v_mov_b32_e32 v219, 0x3fd744fd
.Lres_statdone:
	global_load_dwordx4 v[220:223], v202, s[52:53]
	global_load_dwordx4 v[224:227], v202, s[52:53] offset:16
	global_load_dwordx4 v[228:231], v202, s[52:53] offset:512
	global_load_dwordx4 v[232:235], v202, s[52:53] offset:528
	v_add_u32_e32 v193, 0x1000, v192
	v_add_u32_e32 v194, 0x2000, v192
	v_add_u32_e32 v195, 0x3000, v192
	v_add_u32_e32 v196, 0x80000, v192
	v_add_u32_e32 v197, 0x81000, v192
	v_add_u32_e32 v198, 0x82000, v192
	v_add_u32_e32 v199, 0x83000, v192
	global_load_dwordx4 v[146:149], v192, s[0:1]
	global_load_dwordx4 v[150:153], v192, s[0:1] offset:16
	global_load_dwordx4 v[154:157], v193, s[0:1]
	global_load_dwordx4 v[158:161], v193, s[0:1] offset:16
	global_load_dwordx4 v[162:165], v194, s[0:1]
	global_load_dwordx4 v[166:169], v194, s[0:1] offset:16
	global_load_dwordx4 v[170:173], v195, s[0:1]
	global_load_dwordx4 v[174:177], v195, s[0:1] offset:16
	v_mov_b32_e32 v130, 0
	v_mov_b32_e32 v131, 0
	v_mov_b32_e32 v132, 0
	v_mov_b32_e32 v133, 0
	v_mov_b32_e32 v134, 0
	v_mov_b32_e32 v135, 0
	v_mov_b32_e32 v136, 0
	v_mov_b32_e32 v137, 0
	v_mov_b32_e32 v138, 0
	v_mov_b32_e32 v139, 0
	v_mov_b32_e32 v140, 0
	v_mov_b32_e32 v141, 0
	v_mov_b32_e32 v142, 0
	v_mov_b32_e32 v143, 0
	v_mov_b32_e32 v144, 0
	v_mov_b32_e32 v145, 0
	s_andn2_b64 vcc, exec, s[92:93]
	s_cbranch_vccnz .Lres_nobias
	global_load_dwordx4 v[130:133], v202, s[6:7]
	global_load_dwordx4 v[134:137], v202, s[6:7] offset:16
	global_load_dwordx4 v[138:141], v202, s[6:7] offset:512
	global_load_dwordx4 v[142:145], v202, s[6:7] offset:528
.Lres_nobias:
	s_waitcnt vmcnt(0)
	s_andn2_b64 vcc, exec, s[90:91]
	s_cbranch_vccnz .Lres_noconv
	v_mul_f32_e32 v205, 0x3fd744fd, v205
	v_mul_f32_e32 v207, 0x3fd744fd, v207
	v_mul_f32_e32 v209, 0x3fd744fd, v209
	v_mul_f32_e32 v211, 0x3fd744fd, v211
	v_mul_f32_e32 v213, 0x3fd744fd, v213
	v_mul_f32_e32 v215, 0x3fd744fd, v215
	v_mul_f32_e32 v217, 0x3fd744fd, v217
	v_mul_f32_e32 v219, 0x3fd744fd, v219
	v_mul_f32_e64 v204, v204, -v205
	v_mul_f32_e64 v206, v206, -v207
	v_mul_f32_e64 v208, v208, -v209
	v_mul_f32_e64 v210, v210, -v211
	v_mul_f32_e64 v212, v212, -v213
	v_mul_f32_e64 v214, v214, -v215
	v_mul_f32_e64 v216, v216, -v217
	v_mul_f32_e64 v218, v218, -v219
.Lres_noconv:
	v_fma_f32 v146, v205, v146, v204
	v_fma_f32 v147, v205, v147, v204
	v_fma_f32 v148, v205, v148, v204
	v_fma_f32 v149, v205, v149, v204
	v_fma_f32 v150, v205, v150, v204
	v_fma_f32 v151, v205, v151, v204
	v_fma_f32 v152, v205, v152, v204
	v_fma_f32 v153, v205, v153, v204
	v_fma_f32 v154, v207, v154, v206
	v_fma_f32 v155, v207, v155, v206
	v_fma_f32 v156, v207, v156, v206
	v_fma_f32 v157, v207, v157, v206
	v_fma_f32 v158, v207, v158, v206
	v_fma_f32 v159, v207, v159, v206
	v_fma_f32 v160, v207, v160, v206
	v_fma_f32 v161, v207, v161, v206
	v_fma_f32 v162, v209, v162, v208
	v_fma_f32 v163, v209, v163, v208
	v_fma_f32 v164, v209, v164, v208
	v_fma_f32 v165, v209, v165, v208
	v_fma_f32 v166, v209, v166, v208
	v_fma_f32 v167, v209, v167, v208
	v_fma_f32 v168, v209, v168, v208
	v_fma_f32 v169, v209, v169, v208
	v_fma_f32 v170, v211, v170, v210
	v_fma_f32 v171, v211, v171, v210
	v_fma_f32 v172, v211, v172, v210
	v_fma_f32 v173, v211, v173, v210
	v_fma_f32 v174, v211, v174, v210
	v_fma_f32 v175, v211, v175, v210
	v_fma_f32 v176, v211, v176, v210
	v_fma_f32 v177, v211, v177, v210
	v_add_f32_e32 v126, v126, v130
	v_add_f32_e32 v127, v127, v131
	v_add_f32_e32 v128, v128, v132
	v_add_f32_e32 v129, v129, v133
	v_add_f32_e32 v122, v122, v134
	v_add_f32_e32 v123, v123, v135
	v_add_f32_e32 v124, v124, v136
	v_add_f32_e32 v125, v125, v137
	v_add_f32_e32 v118, v118, v130
	v_add_f32_e32 v119, v119, v131
	v_add_f32_e32 v120, v120, v132
	v_add_f32_e32 v121, v121, v133
	v_add_f32_e32 v114, v114, v134
	v_add_f32_e32 v115, v115, v135
	v_add_f32_e32 v116, v116, v136
	v_add_f32_e32 v117, v117, v137
	v_add_f32_e32 v110, v110, v130
	v_add_f32_e32 v111, v111, v131
	v_add_f32_e32 v112, v112, v132
	v_add_f32_e32 v113, v113, v133
	v_add_f32_e32 v106, v106, v134
	v_add_f32_e32 v107, v107, v135
	v_add_f32_e32 v108, v108, v136
	v_add_f32_e32 v109, v109, v137
	v_add_f32_e32 v102, v102, v130
	v_add_f32_e32 v103, v103, v131
	v_add_f32_e32 v104, v104, v132
	v_add_f32_e32 v105, v105, v133
;     __device__ __forceinline__ void operator()(const f32x4 (&acc)[2][2][4][2], const Unit& u, int wr_in, int wc_in, int fr_in, int fq_in) const {
;     ...
;             for (int bj = 0; bj < 2; ++bj) {
;                 const int col0 = colw + bj * 128;
;                 f32x4 x[4][2];
; #pragma unroll
;                 for (int m = 0; m < 4; ++m) { const float* p = src + (size_t)(rbase + ai * 128 + m) * DM + col0; x[m][0] = *(const f32x4*)(p); x[m][1] = *(const f32x4*)(p + 4); }
;                 const f32x4 g0 = *(const f32x4*)(gp + col0), g1 = *(const f32x4*)(gp + col0 + 4);
;                 f32x4 b0 = (f32x4){0.f, 0.f, 0.f, 0.f}, b1 = b0;
;                 if (bias) { b0 = *(const f32x4*)(bias + col0); b1 = *(const f32x4*)(bias + col0 + 4); }
; #pragma unroll
;                 for (int m = 0; m < 4; ++m) {
;                     float* q = dst + (size_t)(rbase + ai * 128 + m) * DM + col0;
;                     const f32x4 r0 = x[m][0] * sa[m] + sb[m] + g0 * (acc[ai][bj][m][0] + b0), r1 = x[m][1] * sa[m] + sb[m] + g1 * (acc[ai][bj][m][1] + b1);
;                     *(f32x4*)(q) = r0; *(f32x4*)(q + 4) = r1;
;                 }
	v_add_f32_e32 v98, v98, v134
	v_add_f32_e32 v99, v99, v135
	v_add_f32_e32 v100, v100, v136
	v_add_f32_e32 v101, v101, v137
	v_fma_f32 v126, v220, v126, v146
	v_fma_f32 v127, v221, v127, v147
	v_fma_f32 v128, v222, v128, v148
	v_fma_f32 v129, v223, v129, v149
	v_fma_f32 v122, v224, v122, v150
	v_fma_f32 v123, v225, v123, v151
	v_fma_f32 v124, v226, v124, v152
	v_fma_f32 v125, v227, v125, v153
	v_fma_f32 v118, v220, v118, v154
	v_fma_f32 v119, v221, v119, v155
	v_fma_f32 v120, v222, v120, v156
	v_fma_f32 v121, v223, v121, v157
	v_fma_f32 v114, v224, v114, v158
	v_fma_f32 v115, v225, v115, v159
	v_fma_f32 v116, v226, v116, v160
	v_fma_f32 v117, v227, v117, v161
	v_fma_f32 v110, v220, v110, v162
	v_fma_f32 v111, v221, v111, v163
	v_fma_f32 v112, v222, v112, v164
	v_fma_f32 v113, v223, v113, v165
	v_fma_f32 v106, v224, v106, v166
	v_fma_f32 v107, v225, v107, v167
	v_fma_f32 v108, v226, v108, v168
	v_fma_f32 v109, v227, v109, v169
	v_fma_f32 v102, v220, v102, v170
	v_fma_f32 v103, v221, v103, v171
	v_fma_f32 v104, v222, v104, v172
	v_fma_f32 v105, v223, v105, v173
	v_fma_f32 v98, v224, v98, v174
	v_fma_f32 v99, v225, v99, v175
	v_fma_f32 v100, v226, v100, v176
	v_fma_f32 v101, v227, v101, v177
	global_store_dwordx4 v192, v[126:129], s[48:49]
	global_store_dwordx4 v192, v[122:125], s[48:49] offset:16
	global_store_dwordx4 v193, v[118:121], s[48:49]
	global_store_dwordx4 v193, v[114:117], s[48:49] offset:16
	global_store_dwordx4 v194, v[110:113], s[48:49]
	global_store_dwordx4 v194, v[106:109], s[48:49] offset:16
	global_store_dwordx4 v195, v[102:105], s[48:49]
	global_store_dwordx4 v195, v[98:101], s[48:49] offset:16
	global_load_dwordx4 v[146:149], v192, s[0:1] offset:512
	global_load_dwordx4 v[150:153], v192, s[0:1] offset:528
	global_load_dwordx4 v[154:157], v193, s[0:1] offset:512
	global_load_dwordx4 v[158:161], v193, s[0:1] offset:528
	global_load_dwordx4 v[162:165], v194, s[0:1] offset:512
	global_load_dwordx4 v[166:169], v194, s[0:1] offset:528
	global_load_dwordx4 v[170:173], v195, s[0:1] offset:512
	global_load_dwordx4 v[174:177], v195, s[0:1] offset:528
	global_load_dwordx4 v[98:101], v196, s[0:1]
	global_load_dwordx4 v[102:105], v196, s[0:1] offset:16
	global_load_dwordx4 v[106:109], v197, s[0:1]
	global_load_dwordx4 v[110:113], v197, s[0:1] offset:16
	global_load_dwordx4 v[114:117], v198, s[0:1]
	global_load_dwordx4 v[118:121], v198, s[0:1] offset:16
	global_load_dwordx4 v[122:125], v199, s[0:1]
	global_load_dwordx4 v[126:129], v199, s[0:1] offset:16
	s_waitcnt vmcnt(8)
	v_fma_f32 v146, v205, v146, v204
	v_fma_f32 v147, v205, v147, v204
	v_fma_f32 v148, v205, v148, v204
	v_fma_f32 v149, v205, v149, v204
	v_fma_f32 v150, v205, v150, v204
	v_fma_f32 v151, v205, v151, v204
	v_fma_f32 v152, v205, v152, v204
	v_fma_f32 v153, v205, v153, v204
	v_fma_f32 v154, v207, v154, v206
	v_fma_f32 v155, v207, v155, v206
	v_fma_f32 v156, v207, v156, v206
	v_fma_f32 v157, v207, v157, v206
	v_fma_f32 v158, v207, v158, v206
	v_fma_f32 v159, v207, v159, v206
	v_fma_f32 v160, v207, v160, v206
	v_fma_f32 v161, v207, v161, v206
	v_fma_f32 v162, v209, v162, v208
	v_fma_f32 v163, v209, v163, v208
	v_fma_f32 v164, v209, v164, v208
	v_fma_f32 v165, v209, v165, v208
	v_fma_f32 v166, v209, v166, v208
	v_fma_f32 v167, v209, v167, v208
	v_fma_f32 v168, v209, v168, v208
	v_fma_f32 v169, v209, v169, v208
	v_fma_f32 v170, v211, v170, v210
	v_fma_f32 v171, v211, v171, v210
	v_fma_f32 v172, v211, v172, v210
	v_fma_f32 v173, v211, v173, v210
	v_fma_f32 v174, v211, v174, v210
	v_fma_f32 v175, v211, v175, v210
	v_fma_f32 v176, v211, v176, v210
	v_fma_f32 v177, v211, v177, v210
	v_add_f32_e32 v94, v94, v138
	v_add_f32_e32 v95, v95, v139
	v_add_f32_e32 v96, v96, v140
	v_add_f32_e32 v97, v97, v141
	v_add_f32_e32 v90, v90, v142
	v_add_f32_e32 v91, v91, v143
	v_add_f32_e32 v92, v92, v144
	v_add_f32_e32 v93, v93, v145
	v_add_f32_e32 v86, v86, v138
	v_add_f32_e32 v87, v87, v139
	v_add_f32_e32 v88, v88, v140
	v_add_f32_e32 v89, v89, v141
	v_add_f32_e32 v82, v82, v142
	v_add_f32_e32 v83, v83, v143
	v_add_f32_e32 v84, v84, v144
	v_add_f32_e32 v85, v85, v145
	v_add_f32_e32 v78, v78, v138
	v_add_f32_e32 v79, v79, v139
	v_add_f32_e32 v80, v80, v140
	v_add_f32_e32 v81, v81, v141
	v_add_f32_e32 v74, v74, v142
	v_add_f32_e32 v75, v75, v143
	v_add_f32_e32 v76, v76, v144
	v_add_f32_e32 v77, v77, v145
	v_add_f32_e32 v70, v70, v138
	v_add_f32_e32 v71, v71, v139
	v_add_f32_e32 v72, v72, v140
	v_add_f32_e32 v73, v73, v141
	v_add_f32_e32 v66, v66, v142
	v_add_f32_e32 v67, v67, v143
	v_add_f32_e32 v68, v68, v144
	v_add_f32_e32 v69, v69, v145
	v_fma_f32 v94, v228, v94, v146
	v_fma_f32 v95, v229, v95, v147
	v_fma_f32 v96, v230, v96, v148
	v_fma_f32 v97, v231, v97, v149
	v_fma_f32 v90, v232, v90, v150
	v_fma_f32 v91, v233, v91, v151
	v_fma_f32 v92, v234, v92, v152
	v_fma_f32 v93, v235, v93, v153
	v_fma_f32 v86, v228, v86, v154
	v_fma_f32 v87, v229, v87, v155
	v_fma_f32 v88, v230, v88, v156
	v_fma_f32 v89, v231, v89, v157
	v_fma_f32 v82, v232, v82, v158
	v_fma_f32 v83, v233, v83, v159
	v_fma_f32 v84, v234, v84, v160
	v_fma_f32 v85, v235, v85, v161
	v_fma_f32 v78, v228, v78, v162
	v_fma_f32 v79, v229, v79, v163
	v_fma_f32 v80, v230, v80, v164
	v_fma_f32 v81, v231, v81, v165
	v_fma_f32 v74, v232, v74, v166
	v_fma_f32 v75, v233, v75, v167
	v_fma_f32 v76, v234, v76, v168
	v_fma_f32 v77, v235, v77, v169
	v_fma_f32 v70, v228, v70, v170
	v_fma_f32 v71, v229, v71, v171
	v_fma_f32 v72, v230, v72, v172
	v_fma_f32 v73, v231, v73, v173
	v_fma_f32 v66, v232, v66, v174
	v_fma_f32 v67, v233, v67, v175
	v_fma_f32 v68, v234, v68, v176
	v_fma_f32 v69, v235, v69, v177
	global_store_dwordx4 v192, v[94:97], s[48:49] offset:512
	global_store_dwordx4 v192, v[90:93], s[48:49] offset:528
	global_store_dwordx4 v193, v[86:89], s[48:49] offset:512
	global_store_dwordx4 v193, v[82:85], s[48:49] offset:528
	global_store_dwordx4 v194, v[78:81], s[48:49] offset:512
	global_store_dwordx4 v194, v[74:77], s[48:49] offset:528
	global_store_dwordx4 v195, v[70:73], s[48:49] offset:512
	global_store_dwordx4 v195, v[66:69], s[48:49] offset:528
	global_load_dwordx4 v[146:149], v196, s[0:1] offset:512
	global_load_dwordx4 v[150:153], v196, s[0:1] offset:528
	global_load_dwordx4 v[154:157], v197, s[0:1] offset:512
	global_load_dwordx4 v[158:161], v197, s[0:1] offset:528
	global_load_dwordx4 v[162:165], v198, s[0:1] offset:512
	global_load_dwordx4 v[166:169], v198, s[0:1] offset:528
	global_load_dwordx4 v[170:173], v199, s[0:1] offset:512
	global_load_dwordx4 v[174:177], v199, s[0:1] offset:528
	s_waitcnt vmcnt(16)
;     __device__ __forceinline__ void operator()(const f32x4 (&acc)[2][2][4][2], const Unit& u, int wr_in, int wc_in, int fr_in, int fq_in) const {
;     ...
;             for (int bj = 0; bj < 2; ++bj) {
;                 const int col0 = colw + bj * 128;
;                 f32x4 x[4][2];
; #pragma unroll
;                 for (int m = 0; m < 4; ++m) { const float* p = src + (size_t)(rbase + ai * 128 + m) * DM + col0; x[m][0] = *(const f32x4*)(p); x[m][1] = *(const f32x4*)(p + 4); }
;                 const f32x4 g0 = *(const f32x4*)(gp + col0), g1 = *(const f32x4*)(gp + col0 + 4);
;                 f32x4 b0 = (f32x4){0.f, 0.f, 0.f, 0.f}, b1 = b0;
;                 if (bias) { b0 = *(const f32x4*)(bias + col0); b1 = *(const f32x4*)(bias + col0 + 4); }
; #pragma unroll
;                 for (int m = 0; m < 4; ++m) {
;                     float* q = dst + (size_t)(rbase + ai * 128 + m) * DM + col0;
;                     const f32x4 r0 = x[m][0] * sa[m] + sb[m] + g0 * (acc[ai][bj][m][0] + b0), r1 = x[m][1] * sa[m] + sb[m] + g1 * (acc[ai][bj][m][1] + b1);
;                     *(f32x4*)(q) = r0; *(f32x4*)(q + 4) = r1;
;                 }
	v_fma_f32 v98, v213, v98, v212
	v_fma_f32 v99, v213, v99, v212
	v_fma_f32 v100, v213, v100, v212
	v_fma_f32 v101, v213, v101, v212
	v_fma_f32 v102, v213, v102, v212
	v_fma_f32 v103, v213, v103, v212
	v_fma_f32 v104, v213, v104, v212
	v_fma_f32 v105, v213, v105, v212
	v_fma_f32 v106, v215, v106, v214
	v_fma_f32 v107, v215, v107, v214
	v_fma_f32 v108, v215, v108, v214
	v_fma_f32 v109, v215, v109, v214
	v_fma_f32 v110, v215, v110, v214
	v_fma_f32 v111, v215, v111, v214
	v_fma_f32 v112, v215, v112, v214
	v_fma_f32 v113, v215, v113, v214
	v_fma_f32 v114, v217, v114, v216
	v_fma_f32 v115, v217, v115, v216
	v_fma_f32 v116, v217, v116, v216
	v_fma_f32 v117, v217, v117, v216
	v_fma_f32 v118, v217, v118, v216
	v_fma_f32 v119, v217, v119, v216
	v_fma_f32 v120, v217, v120, v216
	v_fma_f32 v121, v217, v121, v216
	v_fma_f32 v122, v219, v122, v218
	v_fma_f32 v123, v219, v123, v218
	v_fma_f32 v124, v219, v124, v218
	v_fma_f32 v125, v219, v125, v218
	v_fma_f32 v126, v219, v126, v218
	v_fma_f32 v127, v219, v127, v218
	v_fma_f32 v128, v219, v128, v218
	v_fma_f32 v129, v219, v129, v218
	v_add_f32_e32 v62, v62, v130
	v_add_f32_e32 v63, v63, v131
	v_add_f32_e32 v64, v64, v132
	v_add_f32_e32 v65, v65, v133
	v_add_f32_e32 v58, v58, v134
	v_add_f32_e32 v59, v59, v135
	v_add_f32_e32 v60, v60, v136
	v_add_f32_e32 v61, v61, v137
	v_add_f32_e32 v54, v54, v130
	v_add_f32_e32 v55, v55, v131
	v_add_f32_e32 v56, v56, v132
	v_add_f32_e32 v57, v57, v133
	v_add_f32_e32 v50, v50, v134
	v_add_f32_e32 v51, v51, v135
	v_add_f32_e32 v52, v52, v136
	v_add_f32_e32 v53, v53, v137
	v_add_f32_e32 v46, v46, v130
	v_add_f32_e32 v47, v47, v131
	v_add_f32_e32 v48, v48, v132
	v_add_f32_e32 v49, v49, v133
	v_add_f32_e32 v42, v42, v134
	v_add_f32_e32 v43, v43, v135
	v_add_f32_e32 v44, v44, v136
	v_add_f32_e32 v45, v45, v137
	v_add_f32_e32 v38, v38, v130
	v_add_f32_e32 v39, v39, v131
	v_add_f32_e32 v40, v40, v132
	v_add_f32_e32 v41, v41, v133
	v_add_f32_e32 v34, v34, v134
	v_add_f32_e32 v35, v35, v135
	v_add_f32_e32 v36, v36, v136
	v_add_f32_e32 v37, v37, v137
	v_fma_f32 v62, v220, v62, v98
	v_fma_f32 v63, v221, v63, v99
	v_fma_f32 v64, v222, v64, v100
	v_fma_f32 v65, v223, v65, v101
	v_fma_f32 v58, v224, v58, v102
	v_fma_f32 v59, v225, v59, v103
	v_fma_f32 v60, v226, v60, v104
	v_fma_f32 v61, v227, v61, v105
	v_fma_f32 v54, v220, v54, v106
	v_fma_f32 v55, v221, v55, v107
	v_fma_f32 v56, v222, v56, v108
	v_fma_f32 v57, v223, v57, v109
	v_fma_f32 v50, v224, v50, v110
	v_fma_f32 v51, v225, v51, v111
	v_fma_f32 v52, v226, v52, v112
	v_fma_f32 v53, v227, v53, v113
	v_fma_f32 v46, v220, v46, v114
	v_fma_f32 v47, v221, v47, v115
	v_fma_f32 v48, v222, v48, v116
	v_fma_f32 v49, v223, v49, v117
	v_fma_f32 v42, v224, v42, v118
	v_fma_f32 v43, v225, v43, v119
	v_fma_f32 v44, v226, v44, v120
	v_fma_f32 v45, v227, v45, v121
	v_fma_f32 v38, v220, v38, v122
	v_fma_f32 v39, v221, v39, v123
	v_fma_f32 v40, v222, v40, v124
	v_fma_f32 v41, v223, v41, v125
	v_fma_f32 v34, v224, v34, v126
	v_fma_f32 v35, v225, v35, v127
	v_fma_f32 v36, v226, v36, v128
	v_fma_f32 v37, v227, v37, v129
	global_store_dwordx4 v196, v[62:65], s[48:49]
	global_store_dwordx4 v196, v[58:61], s[48:49] offset:16
	global_store_dwordx4 v197, v[54:57], s[48:49]
	global_store_dwordx4 v197, v[50:53], s[48:49] offset:16
	global_store_dwordx4 v198, v[46:49], s[48:49]
	global_store_dwordx4 v198, v[42:45], s[48:49] offset:16
	global_store_dwordx4 v199, v[38:41], s[48:49]
	global_store_dwordx4 v199, v[34:37], s[48:49] offset:16
	s_waitcnt vmcnt(8)
; #define PG8_BAR __builtin_amdgcn_s_barrier()
; template <class Epi>
; __device__ __forceinline__ void gemm_phase(LAS unsigned char* lds, const Gemm g, const StaticOrder& S, const Epi& E) {
;     ...
;         cur = nxt; cA = nA; cB = nB; ++ui;
;         if (wr == 1) PG8_BAR;
;     __device__ __forceinline__ void operator()(const f32x4 (&acc)[2][2][4][2], const Unit& u, int wr_in, int wc_in, int fr_in, int fq_in) const {
;     ...
;             for (int bj = 0; bj < 2; ++bj) {
;                 const int col0 = colw + bj * 128;
;                 f32x4 x[4][2];
; #pragma unroll
;                 for (int m = 0; m < 4; ++m) { const float* p = src + (size_t)(rbase + ai * 128 + m) * DM + col0; x[m][0] = *(const f32x4*)(p); x[m][1] = *(const f32x4*)(p + 4); }
;                 const f32x4 g0 = *(const f32x4*)(gp + col0), g1 = *(const f32x4*)(gp + col0 + 4);
;                 f32x4 b0 = (f32x4){0.f, 0.f, 0.f, 0.f}, b1 = b0;
;                 if (bias) { b0 = *(const f32x4*)(bias + col0); b1 = *(const f32x4*)(bias + col0 + 4); }
; #pragma unroll
;                 for (int m = 0; m < 4; ++m) {
;                     float* q = dst + (size_t)(rbase + ai * 128 + m) * DM + col0;
;                     const f32x4 r0 = x[m][0] * sa[m] + sb[m] + g0 * (acc[ai][bj][m][0] + b0), r1 = x[m][1] * sa[m] + sb[m] + g1 * (acc[ai][bj][m][1] + b1);
;                     *(f32x4*)(q) = r0; *(f32x4*)(q + 4) = r1;
;                 }
	v_fma_f32 v146, v213, v146, v212
	v_fma_f32 v147, v213, v147, v212
	v_fma_f32 v148, v213, v148, v212
	v_fma_f32 v149, v213, v149, v212
	v_fma_f32 v150, v213, v150, v212
	v_fma_f32 v151, v213, v151, v212
	v_fma_f32 v152, v213, v152, v212
	v_fma_f32 v153, v213, v153, v212
	v_fma_f32 v154, v215, v154, v214
	v_fma_f32 v155, v215, v155, v214
	v_fma_f32 v156, v215, v156, v214
	v_fma_f32 v157, v215, v157, v214
	v_fma_f32 v158, v215, v158, v214
	v_fma_f32 v159, v215, v159, v214
	v_fma_f32 v160, v215, v160, v214
	v_fma_f32 v161, v215, v161, v214
	v_fma_f32 v162, v217, v162, v216
	v_fma_f32 v163, v217, v163, v216
	v_fma_f32 v164, v217, v164, v216
	v_fma_f32 v165, v217, v165, v216
	v_fma_f32 v166, v217, v166, v216
	v_fma_f32 v167, v217, v167, v216
	v_fma_f32 v168, v217, v168, v216
	v_fma_f32 v169, v217, v169, v216
	v_fma_f32 v170, v219, v170, v218
	v_fma_f32 v171, v219, v171, v218
	v_fma_f32 v172, v219, v172, v218
	v_fma_f32 v173, v219, v173, v218
	v_fma_f32 v174, v219, v174, v218
	v_fma_f32 v175, v219, v175, v218
	v_fma_f32 v176, v219, v176, v218
	v_fma_f32 v177, v219, v177, v218
	v_add_f32_e32 v30, v30, v138
	v_add_f32_e32 v31, v31, v139
	v_add_f32_e32 v32, v32, v140
	v_add_f32_e32 v33, v33, v141
	v_add_f32_e32 v26, v26, v142
	v_add_f32_e32 v27, v27, v143
	v_add_f32_e32 v28, v28, v144
	v_add_f32_e32 v29, v29, v145
	v_add_f32_e32 v22, v22, v138
	v_add_f32_e32 v23, v23, v139
	v_add_f32_e32 v24, v24, v140
	v_add_f32_e32 v25, v25, v141
	v_add_f32_e32 v18, v18, v142
	v_add_f32_e32 v19, v19, v143
	v_add_f32_e32 v20, v20, v144
	v_add_f32_e32 v21, v21, v145
	v_add_f32_e32 v14, v14, v138
	v_add_f32_e32 v15, v15, v139
	v_add_f32_e32 v16, v16, v140
	v_add_f32_e32 v17, v17, v141
	v_add_f32_e32 v10, v10, v142
	v_add_f32_e32 v11, v11, v143
	v_add_f32_e32 v12, v12, v144
	v_add_f32_e32 v13, v13, v145
	v_add_f32_e32 v6, v6, v138
	v_add_f32_e32 v7, v7, v139
	v_add_f32_e32 v8, v8, v140
	v_add_f32_e32 v9, v9, v141
	v_add_f32_e32 v2, v2, v142
	v_add_f32_e32 v3, v3, v143
	v_add_f32_e32 v4, v4, v144
	v_add_f32_e32 v5, v5, v145
	v_fma_f32 v30, v228, v30, v146
	v_fma_f32 v31, v229, v31, v147
	v_fma_f32 v32, v230, v32, v148
	v_fma_f32 v33, v231, v33, v149
	v_fma_f32 v26, v232, v26, v150
	v_fma_f32 v27, v233, v27, v151
	v_fma_f32 v28, v234, v28, v152
	v_fma_f32 v29, v235, v29, v153
	v_fma_f32 v22, v228, v22, v154
	v_fma_f32 v23, v229, v23, v155
	v_fma_f32 v24, v230, v24, v156
	v_fma_f32 v25, v231, v25, v157
	v_fma_f32 v18, v232, v18, v158
	v_fma_f32 v19, v233, v19, v159
	v_fma_f32 v20, v234, v20, v160
	v_fma_f32 v21, v235, v21, v161
	v_fma_f32 v14, v228, v14, v162
	v_fma_f32 v15, v229, v15, v163
	v_fma_f32 v16, v230, v16, v164
	v_fma_f32 v17, v231, v17, v165
	v_fma_f32 v10, v232, v10, v166
	v_fma_f32 v11, v233, v11, v167
	v_fma_f32 v12, v234, v12, v168
	v_fma_f32 v13, v235, v13, v169
	v_fma_f32 v6, v228, v6, v170
	v_fma_f32 v7, v229, v7, v171
	v_fma_f32 v8, v230, v8, v172
	v_fma_f32 v9, v231, v9, v173
	v_fma_f32 v2, v232, v2, v174
	v_fma_f32 v3, v233, v3, v175
	v_fma_f32 v4, v234, v4, v176
	v_fma_f32 v5, v235, v5, v177
	global_store_dwordx4 v196, v[30:33], s[48:49] offset:512
	global_store_dwordx4 v196, v[26:29], s[48:49] offset:528
	global_store_dwordx4 v197, v[22:25], s[48:49] offset:512
	global_store_dwordx4 v197, v[18:21], s[48:49] offset:528
	global_store_dwordx4 v198, v[14:17], s[48:49] offset:512
	global_store_dwordx4 v198, v[10:13], s[48:49] offset:528
	global_store_dwordx4 v199, v[6:9], s[48:49] offset:512
	global_store_dwordx4 v199, v[2:5], s[48:49] offset:528
	s_and_b64 vcc, exec, s[38:39]
	s_mov_b64 s[0:1], -1
	s_cbranch_vccnz .LBB0_300
	s_andn2_b64 vcc, exec, s[82:83]
	s_cbranch_vccnz .LBB0_299
	s_barrier
	s_branch .LBB0_299

; __device__ __forceinline__ void xcd_barrier(const XcdBarrier& b) {
;     asm volatile("s_waitcnt vmcnt(0)" ::: "memory");
;     __syncthreads();
;     if (threadIdx.x == 0) {
;         unsigned* bar = b.bar;
;         __builtin_amdgcn_s_waitcnt(0);
;         unsigned nloc = b.st[0], nx = b.st[1];
;         if (nloc == 0u) { xcd_barrier_complete(bar, b.x, nloc, nx); b.st[0] = nloc; b.st[1] = nx; }
; __global__ void __launch_bounds__(512, 2) mk_fwd(Args args) {
;     ...
;         if (ph + 1 < args.ph_hi) { if (ph == 0) grid.sync(); else xcd_barrier(xbar); }
.LBB0_625:
	v_readlane_b32 s0, v254, 10
	v_readlane_b32 s1, v254, 11
	s_and_b64 vcc, exec, s[0:1]
	s_waitcnt vmcnt(0)
	s_waitcnt vmcnt(0) lgkmcnt(0)
	s_barrier
	s_mov_b64 s[0:1], exec
	v_readlane_b32 s2, v252, 18
	v_readlane_b32 s3, v252, 19
	s_and_b64 s[2:3], s[0:1], s[2:3]
	s_mov_b64 exec, s[2:3]
	s_cbranch_execz .LBB0_681
	v_readlane_b32 s2, v253, 26
	s_waitcnt vmcnt(0) expcnt(0) lgkmcnt(0)
	s_nop 0
	v_mov_b32_e32 v0, s2
	ds_read_b32 v3, v0
	v_readlane_b32 s2, v253, 27
	s_waitcnt lgkmcnt(0)
	v_cmp_ne_u32_e32 vcc, 0, v3
	v_mov_b32_e32 v0, s2
	ds_read_b32 v2, v0
	s_cbranch_vccnz .LBB0_643
	s_mov_b32 s2, 1
	s_branch .LBB0_630

; __device__ __forceinline__ unsigned xb_ld(unsigned* p)              { return __hip_atomic_load(p, __ATOMIC_RELAXED, __HIP_MEMORY_SCOPE_AGENT); }
; __device__ __forceinline__ void xcd_barrier_complete(unsigned* bar, unsigned x, unsigned& nloc, unsigned& nx) {
;     const unsigned G = gridDim.x * gridDim.y * gridDim.z;
;     unsigned sum, cnt, mine, sp = 0u;
;     for (;;) {
;         sum = 0u; cnt = 0u; mine = 0u;
; #pragma unroll
;         for (unsigned j = 0; j < 16; ++j) { const unsigned c = xb_ld(&bar[XB_XCNT(j)]); sum += c; cnt += (c > 0u) ? 1u : 0u; mine = (j == x) ? c : mine; }
;         if (sum == G) break;
;         __builtin_amdgcn_s_sleep(1);
;         if ((++sp & 255u) == 0u) { if (xb_ld(&bar[XB_TMO])) break; if (sp > XB_SPIN_CAP) { atomicAdd(&bar[XB_TMO], 1u); break; } }
;     }
;     nloc = mine > 0u ? mine : 1u; nx = cnt > 0u ? cnt : 1u;
; }
.LBB0_636:
	s_cmp_lt_u32 s2, 0x40001
	s_mov_b64 s[4:5], 0
	s_cselect_b64 s[8:9], -1, 0
	s_and_b64 vcc, exec, s[8:9]
	s_cbranch_vccz .LBB0_629
	s_branch .LBB0_635
.LBB0_638:
	s_andn2_b64 vcc, exec, s[4:5]
	s_cbranch_vccz .LBB0_642
	s_mov_b64 s[6:7], exec
	v_mbcnt_lo_u32_b32 v17, s6, 0
	v_mbcnt_hi_u32_b32 v17, s7, v17
	v_cmp_eq_u32_e32 vcc, 0, v17
	s_and_saveexec_b64 s[4:5], vcc
	s_cbranch_execz .LBB0_641
	s_bcnt1_i32_b64 s2, s[6:7]
	v_mov_b32_e32 v17, s2
	v_readlane_b32 s2, v252, 32
	v_readlane_b32 s3, v252, 33
	s_nop 4
	global_atomic_add v1, v17, s[2:3]

; __device__ __forceinline__ void xcd_barrier(const XcdBarrier& b) {
;     ...
;     }
;     __syncthreads();
; }
; __global__ void __launch_bounds__(512, 2) mk_fwd(Args args) {
;     ...
;         if (ph + 1 < args.ph_hi) { if (ph == 0) grid.sync(); else xcd_barrier(xbar); }
.LBB0_681:
	s_or_b64 exec, exec, s[0:1]
	s_waitcnt lgkmcnt(0)
	s_barrier
	s_branch .LBB0_9
.LBB0_691:
	s_mov_b64 s[66:67], 0
